# v23: SwiGLU (GU) epilogue arithmetic rewritten with packed f32 ops on natural column pairs (same operations/order/rounding, 90->52 VALU per 16-acc block)
# speedup vs baseline: 1.0113x; 1.0113x over previous
; __device__ __forceinline__ u32x4 pack8(const f32x4 a, const f32x4 b) { u32x4 w; w.x = cvt_pk_bf16(a[0], a[1]); w.y = cvt_pk_bf16(a[2], a[3]); w.z = cvt_pk_bf16(b[0], b[1]); w.w = cvt_pk_bf16(b[2], b[3]); return w; }
;     __device__ __forceinline__ void operator()(const f32x4 (&acc)[2][2][4][2], const Unit& u, int wr, int wc, int fr, int fq) const {
;     ...
;                 const float rs = R[ai * HALF + wr * 64 + m * 16 + fr];
;                 bf16_t* ACT = (bf16_t*)(ws + WS_ACT);
;                 f32x4 a[2];
; #pragma unroll
;                 for (int n = 0; n < 2; ++n) {
;                     const f32x4 g = acc[ai][0][m][n] * rs, uu = acc[ai][1][m][n] * rs;
; #pragma unroll
;                     for (int j = 0; j < 4; ++j) a[n][j] = g[j] * __builtin_amdgcn_rcpf(1.0f + __builtin_amdgcn_exp2f(-1.4426950408889634f * g[j])) * uu[j];
;                 }
;                 *(u32x4*)(ACT + (size_t)row * 2816 + u.pn * 128 + wc * 32 + 8 * fq) = pack8(a[0], a[1]);
.LBB0_38:
	s_lshl_b32 s3, s48, 8
	ds_read_b32 v146, v142
	v_mov_b32_e32 v145, 0xbfb8aa3b
	s_waitcnt lgkmcnt(0)
	v_pk_mul_f32 v[124:125], v[124:125], v[146:147] op_sel_hi:[1,0]
	v_pk_mul_f32 v[126:127], v[126:127], v[146:147] op_sel_hi:[1,0]
	v_pk_mul_f32 v[116:117], v[116:117], v[146:147] op_sel_hi:[1,0]
	v_pk_mul_f32 v[118:119], v[118:119], v[146:147] op_sel_hi:[1,0]
	v_pk_mul_f32 v[120:121], v[120:121], v[146:147] op_sel_hi:[1,0]
	v_pk_mul_f32 v[122:123], v[122:123], v[146:147] op_sel_hi:[1,0]
	v_pk_mul_f32 v[112:113], v[112:113], v[146:147] op_sel_hi:[1,0]
	v_pk_mul_f32 v[114:115], v[114:115], v[146:147] op_sel_hi:[1,0]
	v_pk_mul_f32 v[148:149], v[124:125], v[144:145] op_sel:[0,1] op_sel_hi:[1,1]
	v_exp_f32_e32 v148, v148
	v_exp_f32_e32 v149, v149
	v_add_f32_e32 v148, 1.0, v148
	v_add_f32_e32 v149, 1.0, v149
	v_rcp_f32_e32 v148, v148
	v_rcp_f32_e32 v149, v149
	s_nop 0
	v_pk_mul_f32 v[124:125], v[124:125], v[148:149]
	v_pk_mul_f32 v[120:121], v[120:121], v[124:125]
	v_pk_mul_f32 v[148:149], v[126:127], v[144:145] op_sel:[0,1] op_sel_hi:[1,1]
	v_exp_f32_e32 v148, v148
	v_exp_f32_e32 v149, v149
	v_add_f32_e32 v148, 1.0, v148
	v_add_f32_e32 v149, 1.0, v149
	v_rcp_f32_e32 v148, v148
	v_rcp_f32_e32 v149, v149
	s_nop 0
	v_pk_mul_f32 v[126:127], v[126:127], v[148:149]
	v_pk_mul_f32 v[122:123], v[122:123], v[126:127]
	v_pk_mul_f32 v[148:149], v[116:117], v[144:145] op_sel:[0,1] op_sel_hi:[1,1]
	v_exp_f32_e32 v148, v148
	v_exp_f32_e32 v149, v149
	v_add_f32_e32 v148, 1.0, v148
	v_add_f32_e32 v149, 1.0, v149
	v_rcp_f32_e32 v148, v148
	v_rcp_f32_e32 v149, v149
	s_nop 0
	v_pk_mul_f32 v[116:117], v[116:117], v[148:149]
	v_pk_mul_f32 v[112:113], v[112:113], v[116:117]
	v_pk_mul_f32 v[148:149], v[118:119], v[144:145] op_sel:[0,1] op_sel_hi:[1,1]
	v_exp_f32_e32 v148, v148
	v_exp_f32_e32 v149, v149
	v_add_f32_e32 v148, 1.0, v148
	v_add_f32_e32 v149, 1.0, v149
	v_rcp_f32_e32 v148, v148
	v_rcp_f32_e32 v149, v149
	s_nop 0
	v_pk_mul_f32 v[118:119], v[118:119], v[148:149]
	v_pk_mul_f32 v[114:115], v[114:115], v[118:119]
	v_cvt_pk_bf16_f32 v116, v112, v113
	v_cvt_pk_bf16_f32 v117, v114, v115
	v_cvt_pk_bf16_f32 v114, v120, v121
	v_cvt_pk_bf16_f32 v115, v122, v123
	s_lshl_b32 s0, s47, 7
	v_add_u32_e32 v144, s3, v140
	s_ashr_i32 s1, s0, 31
	s_movk_i32 s3, 0x1600
	s_lshl_b64 s[0:1], s[0:1], 1
	s_andn2_b64 vcc, exec, s[36:37]
	v_mov_b64_e32 v[112:113], s[16:17]
	v_mad_i64_i32 v[118:119], s[4:5], v144, s3, v[112:113]
	v_lshl_add_u64 v[118:119], v[118:119], 0, s[0:1]
	v_lshl_add_u64 v[118:119], v[118:119], 0, s[34:35]
	v_lshl_add_u64 v[118:119], v[118:119], 0, v[184:185]
	global_store_dwordx4 v[118:119], v[114:117], off
	ds_read_b32 v114, v142 offset:64
	s_waitcnt lgkmcnt(0)
	v_pk_mul_f32 v[108:109], v[108:109], v[114:115] op_sel_hi:[1,0]
	v_pk_mul_f32 v[110:111], v[110:111], v[114:115] op_sel_hi:[1,0]
	v_pk_mul_f32 v[100:101], v[100:101], v[114:115] op_sel_hi:[1,0]
	v_pk_mul_f32 v[102:103], v[102:103], v[114:115] op_sel_hi:[1,0]
	v_pk_mul_f32 v[104:105], v[104:105], v[114:115] op_sel_hi:[1,0]
	v_pk_mul_f32 v[106:107], v[106:107], v[114:115] op_sel_hi:[1,0]
	v_pk_mul_f32 v[96:97], v[96:97], v[114:115] op_sel_hi:[1,0]
	v_pk_mul_f32 v[98:99], v[98:99], v[114:115] op_sel_hi:[1,0]
	v_pk_mul_f32 v[148:149], v[108:109], v[144:145] op_sel:[0,1] op_sel_hi:[1,1]
	v_exp_f32_e32 v148, v148
	v_exp_f32_e32 v149, v149
	v_add_f32_e32 v148, 1.0, v148
	v_add_f32_e32 v149, 1.0, v149
	v_rcp_f32_e32 v148, v148
	v_rcp_f32_e32 v149, v149
	s_nop 0
	v_pk_mul_f32 v[108:109], v[108:109], v[148:149]
	v_pk_mul_f32 v[104:105], v[104:105], v[108:109]
	v_pk_mul_f32 v[148:149], v[110:111], v[144:145] op_sel:[0,1] op_sel_hi:[1,1]
	v_exp_f32_e32 v148, v148
	v_exp_f32_e32 v149, v149
	v_add_f32_e32 v148, 1.0, v148
	v_add_f32_e32 v149, 1.0, v149
	v_rcp_f32_e32 v148, v148
	v_rcp_f32_e32 v149, v149
	s_nop 0
	v_pk_mul_f32 v[110:111], v[110:111], v[148:149]
	v_pk_mul_f32 v[106:107], v[106:107], v[110:111]
	v_pk_mul_f32 v[148:149], v[100:101], v[144:145] op_sel:[0,1] op_sel_hi:[1,1]
	v_exp_f32_e32 v148, v148
	v_exp_f32_e32 v149, v149
	v_add_f32_e32 v148, 1.0, v148
	v_add_f32_e32 v149, 1.0, v149
	v_rcp_f32_e32 v148, v148
	v_rcp_f32_e32 v149, v149
	s_nop 0
	v_pk_mul_f32 v[100:101], v[100:101], v[148:149]
	v_pk_mul_f32 v[96:97], v[96:97], v[100:101]
	v_pk_mul_f32 v[148:149], v[102:103], v[144:145] op_sel:[0,1] op_sel_hi:[1,1]
	v_exp_f32_e32 v148, v148
	v_exp_f32_e32 v149, v149
	v_add_f32_e32 v148, 1.0, v148
	v_add_f32_e32 v149, 1.0, v149
	v_rcp_f32_e32 v148, v148
	v_rcp_f32_e32 v149, v149
	s_nop 0
	v_pk_mul_f32 v[102:103], v[102:103], v[148:149]
	v_pk_mul_f32 v[98:99], v[98:99], v[102:103]
	v_cvt_pk_bf16_f32 v99, v98, v99
	v_cvt_pk_bf16_f32 v98, v96, v97
	v_cvt_pk_bf16_f32 v96, v104, v105
	v_cvt_pk_bf16_f32 v97, v106, v107
	v_or_b32_e32 v102, 16, v144
	v_mad_i64_i32 v[100:101], s[4:5], v102, s3, v[112:113]
	v_lshl_add_u64 v[100:101], v[100:101], 0, s[0:1]
	v_lshl_add_u64 v[100:101], v[100:101], 0, s[34:35]
	v_lshl_add_u64 v[100:101], v[100:101], 0, v[184:185]
	global_store_dwordx4 v[100:101], v[96:99], off
	ds_read_b32 v96, v142 offset:128
	s_waitcnt lgkmcnt(0)
; __device__ __forceinline__ u32x4 pack8(const f32x4 a, const f32x4 b) { u32x4 w; w.x = cvt_pk_bf16(a[0], a[1]); w.y = cvt_pk_bf16(a[2], a[3]); w.z = cvt_pk_bf16(b[0], b[1]); w.w = cvt_pk_bf16(b[2], b[3]); return w; }
;     __device__ __forceinline__ void operator()(const f32x4 (&acc)[2][2][4][2], const Unit& u, int wr, int wc, int fr, int fq) const {
;     ...
;                 const float rs = R[ai * HALF + wr * 64 + m * 16 + fr];
;                 bf16_t* ACT = (bf16_t*)(ws + WS_ACT);
;                 f32x4 a[2];
; #pragma unroll
;                 for (int n = 0; n < 2; ++n) {
;                     const f32x4 g = acc[ai][0][m][n] * rs, uu = acc[ai][1][m][n] * rs;
; #pragma unroll
;                     for (int j = 0; j < 4; ++j) a[n][j] = g[j] * __builtin_amdgcn_rcpf(1.0f + __builtin_amdgcn_exp2f(-1.4426950408889634f * g[j])) * uu[j];
;                 }
;                 *(u32x4*)(ACT + (size_t)row * 2816 + u.pn * 128 + wc * 32 + 8 * fq) = pack8(a[0], a[1]);
	v_pk_mul_f32 v[92:93], v[92:93], v[96:97] op_sel_hi:[1,0]
	v_pk_mul_f32 v[94:95], v[94:95], v[96:97] op_sel_hi:[1,0]
	v_pk_mul_f32 v[84:85], v[84:85], v[96:97] op_sel_hi:[1,0]
	v_pk_mul_f32 v[86:87], v[86:87], v[96:97] op_sel_hi:[1,0]
	v_pk_mul_f32 v[88:89], v[88:89], v[96:97] op_sel_hi:[1,0]
	v_pk_mul_f32 v[90:91], v[90:91], v[96:97] op_sel_hi:[1,0]
	v_pk_mul_f32 v[80:81], v[80:81], v[96:97] op_sel_hi:[1,0]
	v_pk_mul_f32 v[82:83], v[82:83], v[96:97] op_sel_hi:[1,0]
	v_pk_mul_f32 v[148:149], v[92:93], v[144:145] op_sel:[0,1] op_sel_hi:[1,1]
	v_exp_f32_e32 v148, v148
	v_exp_f32_e32 v149, v149
	v_add_f32_e32 v148, 1.0, v148
	v_add_f32_e32 v149, 1.0, v149
	v_rcp_f32_e32 v148, v148
	v_rcp_f32_e32 v149, v149
	s_nop 0
	v_pk_mul_f32 v[92:93], v[92:93], v[148:149]
	v_pk_mul_f32 v[88:89], v[88:89], v[92:93]
	v_pk_mul_f32 v[148:149], v[94:95], v[144:145] op_sel:[0,1] op_sel_hi:[1,1]
	v_exp_f32_e32 v148, v148
	v_exp_f32_e32 v149, v149
	v_add_f32_e32 v148, 1.0, v148
	v_add_f32_e32 v149, 1.0, v149
	v_rcp_f32_e32 v148, v148
	v_rcp_f32_e32 v149, v149
	s_nop 0
	v_pk_mul_f32 v[94:95], v[94:95], v[148:149]
	v_pk_mul_f32 v[90:91], v[90:91], v[94:95]
	v_pk_mul_f32 v[148:149], v[84:85], v[144:145] op_sel:[0,1] op_sel_hi:[1,1]
	v_exp_f32_e32 v148, v148
	v_exp_f32_e32 v149, v149
	v_add_f32_e32 v148, 1.0, v148
	v_add_f32_e32 v149, 1.0, v149
	v_rcp_f32_e32 v148, v148
	v_rcp_f32_e32 v149, v149
	s_nop 0
	v_pk_mul_f32 v[84:85], v[84:85], v[148:149]
	v_pk_mul_f32 v[80:81], v[80:81], v[84:85]
	v_pk_mul_f32 v[148:149], v[86:87], v[144:145] op_sel:[0,1] op_sel_hi:[1,1]
	v_exp_f32_e32 v148, v148
	v_exp_f32_e32 v149, v149
	v_add_f32_e32 v148, 1.0, v148
	v_add_f32_e32 v149, 1.0, v149
	v_rcp_f32_e32 v148, v148
	v_rcp_f32_e32 v149, v149
	s_nop 0
	v_pk_mul_f32 v[86:87], v[86:87], v[148:149]
	v_pk_mul_f32 v[82:83], v[82:83], v[86:87]
	v_cvt_pk_bf16_f32 v83, v82, v83
	v_cvt_pk_bf16_f32 v82, v80, v81
	v_cvt_pk_bf16_f32 v80, v88, v89
	v_cvt_pk_bf16_f32 v81, v90, v91
	v_or_b32_e32 v86, 32, v144
	v_mad_i64_i32 v[84:85], s[4:5], v86, s3, v[112:113]
	v_lshl_add_u64 v[84:85], v[84:85], 0, s[0:1]
	v_lshl_add_u64 v[84:85], v[84:85], 0, s[34:35]
	v_lshl_add_u64 v[84:85], v[84:85], 0, v[184:185]
	global_store_dwordx4 v[84:85], v[80:83], off
	ds_read_b32 v80, v142 offset:192
	s_waitcnt lgkmcnt(0)
	v_pk_mul_f32 v[76:77], v[76:77], v[80:81] op_sel_hi:[1,0]
	v_pk_mul_f32 v[78:79], v[78:79], v[80:81] op_sel_hi:[1,0]
	v_pk_mul_f32 v[68:69], v[68:69], v[80:81] op_sel_hi:[1,0]
	v_pk_mul_f32 v[70:71], v[70:71], v[80:81] op_sel_hi:[1,0]
	v_pk_mul_f32 v[72:73], v[72:73], v[80:81] op_sel_hi:[1,0]
	v_pk_mul_f32 v[74:75], v[74:75], v[80:81] op_sel_hi:[1,0]
	v_pk_mul_f32 v[64:65], v[64:65], v[80:81] op_sel_hi:[1,0]
	v_pk_mul_f32 v[66:67], v[66:67], v[80:81] op_sel_hi:[1,0]
	v_pk_mul_f32 v[148:149], v[76:77], v[144:145] op_sel:[0,1] op_sel_hi:[1,1]
	v_exp_f32_e32 v148, v148
	v_exp_f32_e32 v149, v149
	v_add_f32_e32 v148, 1.0, v148
	v_add_f32_e32 v149, 1.0, v149
	v_rcp_f32_e32 v148, v148
	v_rcp_f32_e32 v149, v149
	s_nop 0
	v_pk_mul_f32 v[76:77], v[76:77], v[148:149]
	v_pk_mul_f32 v[72:73], v[72:73], v[76:77]
	v_pk_mul_f32 v[148:149], v[78:79], v[144:145] op_sel:[0,1] op_sel_hi:[1,1]
	v_exp_f32_e32 v148, v148
	v_exp_f32_e32 v149, v149
	v_add_f32_e32 v148, 1.0, v148
	v_add_f32_e32 v149, 1.0, v149
	v_rcp_f32_e32 v148, v148
	v_rcp_f32_e32 v149, v149
	s_nop 0
	v_pk_mul_f32 v[78:79], v[78:79], v[148:149]
	v_pk_mul_f32 v[74:75], v[74:75], v[78:79]
	v_pk_mul_f32 v[148:149], v[68:69], v[144:145] op_sel:[0,1] op_sel_hi:[1,1]
	v_exp_f32_e32 v148, v148
	v_exp_f32_e32 v149, v149
	v_add_f32_e32 v148, 1.0, v148
	v_add_f32_e32 v149, 1.0, v149
	v_rcp_f32_e32 v148, v148
	v_rcp_f32_e32 v149, v149
	s_nop 0
	v_pk_mul_f32 v[68:69], v[68:69], v[148:149]
	v_pk_mul_f32 v[64:65], v[64:65], v[68:69]
	v_pk_mul_f32 v[148:149], v[70:71], v[144:145] op_sel:[0,1] op_sel_hi:[1,1]
	v_exp_f32_e32 v148, v148
	v_exp_f32_e32 v149, v149
	v_add_f32_e32 v148, 1.0, v148
	v_add_f32_e32 v149, 1.0, v149
	v_rcp_f32_e32 v148, v148
	v_rcp_f32_e32 v149, v149
	s_nop 0
	v_pk_mul_f32 v[70:71], v[70:71], v[148:149]
	v_pk_mul_f32 v[66:67], v[66:67], v[70:71]
	v_cvt_pk_bf16_f32 v67, v66, v67
	v_cvt_pk_bf16_f32 v66, v64, v65
	v_cvt_pk_bf16_f32 v64, v72, v73
	v_cvt_pk_bf16_f32 v65, v74, v75
	v_or_b32_e32 v70, 48, v144
	v_mad_i64_i32 v[68:69], s[4:5], v70, s3, v[112:113]
	v_lshl_add_u64 v[68:69], v[68:69], 0, s[0:1]
	v_lshl_add_u64 v[68:69], v[68:69], 0, s[34:35]
	v_lshl_add_u64 v[68:69], v[68:69], 0, v[184:185]
	global_store_dwordx4 v[68:69], v[64:67], off
	ds_read_b32 v64, v142 offset:512
	s_waitcnt lgkmcnt(0)
; __device__ __forceinline__ u32x4 pack8(const f32x4 a, const f32x4 b) { u32x4 w; w.x = cvt_pk_bf16(a[0], a[1]); w.y = cvt_pk_bf16(a[2], a[3]); w.z = cvt_pk_bf16(b[0], b[1]); w.w = cvt_pk_bf16(b[2], b[3]); return w; }
;     __device__ __forceinline__ void operator()(const f32x4 (&acc)[2][2][4][2], const Unit& u, int wr, int wc, int fr, int fq) const {
;     ...
;                 const float rs = R[ai * HALF + wr * 64 + m * 16 + fr];
;                 bf16_t* ACT = (bf16_t*)(ws + WS_ACT);
;                 f32x4 a[2];
; #pragma unroll
;                 for (int n = 0; n < 2; ++n) {
;                     const f32x4 g = acc[ai][0][m][n] * rs, uu = acc[ai][1][m][n] * rs;
; #pragma unroll
;                     for (int j = 0; j < 4; ++j) a[n][j] = g[j] * __builtin_amdgcn_rcpf(1.0f + __builtin_amdgcn_exp2f(-1.4426950408889634f * g[j])) * uu[j];
;                 }
;                 *(u32x4*)(ACT + (size_t)row * 2816 + u.pn * 128 + wc * 32 + 8 * fq) = pack8(a[0], a[1]);
	v_pk_mul_f32 v[60:61], v[60:61], v[64:65] op_sel_hi:[1,0]
	v_pk_mul_f32 v[62:63], v[62:63], v[64:65] op_sel_hi:[1,0]
	v_pk_mul_f32 v[52:53], v[52:53], v[64:65] op_sel_hi:[1,0]
	v_pk_mul_f32 v[54:55], v[54:55], v[64:65] op_sel_hi:[1,0]
	v_pk_mul_f32 v[56:57], v[56:57], v[64:65] op_sel_hi:[1,0]
	v_pk_mul_f32 v[58:59], v[58:59], v[64:65] op_sel_hi:[1,0]
	v_pk_mul_f32 v[48:49], v[48:49], v[64:65] op_sel_hi:[1,0]
	v_pk_mul_f32 v[50:51], v[50:51], v[64:65] op_sel_hi:[1,0]
	v_pk_mul_f32 v[148:149], v[60:61], v[144:145] op_sel:[0,1] op_sel_hi:[1,1]
	v_exp_f32_e32 v148, v148
	v_exp_f32_e32 v149, v149
	v_add_f32_e32 v148, 1.0, v148
	v_add_f32_e32 v149, 1.0, v149
	v_rcp_f32_e32 v148, v148
	v_rcp_f32_e32 v149, v149
	s_nop 0
	v_pk_mul_f32 v[60:61], v[60:61], v[148:149]
	v_pk_mul_f32 v[56:57], v[56:57], v[60:61]
	v_pk_mul_f32 v[148:149], v[62:63], v[144:145] op_sel:[0,1] op_sel_hi:[1,1]
	v_exp_f32_e32 v148, v148
	v_exp_f32_e32 v149, v149
	v_add_f32_e32 v148, 1.0, v148
	v_add_f32_e32 v149, 1.0, v149
	v_rcp_f32_e32 v148, v148
	v_rcp_f32_e32 v149, v149
	s_nop 0
	v_pk_mul_f32 v[62:63], v[62:63], v[148:149]
	v_pk_mul_f32 v[58:59], v[58:59], v[62:63]
	v_pk_mul_f32 v[148:149], v[52:53], v[144:145] op_sel:[0,1] op_sel_hi:[1,1]
	v_exp_f32_e32 v148, v148
	v_exp_f32_e32 v149, v149
	v_add_f32_e32 v148, 1.0, v148
	v_add_f32_e32 v149, 1.0, v149
	v_rcp_f32_e32 v148, v148
	v_rcp_f32_e32 v149, v149
	s_nop 0
	v_pk_mul_f32 v[52:53], v[52:53], v[148:149]
	v_pk_mul_f32 v[48:49], v[48:49], v[52:53]
	v_pk_mul_f32 v[148:149], v[54:55], v[144:145] op_sel:[0,1] op_sel_hi:[1,1]
	v_exp_f32_e32 v148, v148
	v_exp_f32_e32 v149, v149
	v_add_f32_e32 v148, 1.0, v148
	v_add_f32_e32 v149, 1.0, v149
	v_rcp_f32_e32 v148, v148
	v_rcp_f32_e32 v149, v149
	s_nop 0
	v_pk_mul_f32 v[54:55], v[54:55], v[148:149]
	v_pk_mul_f32 v[50:51], v[50:51], v[54:55]
	v_cvt_pk_bf16_f32 v51, v50, v51
	v_cvt_pk_bf16_f32 v50, v48, v49
	v_cvt_pk_bf16_f32 v48, v56, v57
	v_cvt_pk_bf16_f32 v49, v58, v59
	v_add_u32_e32 v65, 0x80, v144
	v_mad_i64_i32 v[52:53], s[4:5], v65, s3, v[112:113]
	v_lshl_add_u64 v[52:53], v[52:53], 0, s[0:1]
	v_lshl_add_u64 v[52:53], v[52:53], 0, s[34:35]
	v_lshl_add_u64 v[52:53], v[52:53], 0, v[184:185]
	global_store_dwordx4 v[52:53], v[48:51], off
	ds_read_b32 v48, v142 offset:576
	s_waitcnt lgkmcnt(0)
	v_pk_mul_f32 v[44:45], v[44:45], v[48:49] op_sel_hi:[1,0]
	v_pk_mul_f32 v[46:47], v[46:47], v[48:49] op_sel_hi:[1,0]
	v_pk_mul_f32 v[36:37], v[36:37], v[48:49] op_sel_hi:[1,0]
	v_pk_mul_f32 v[38:39], v[38:39], v[48:49] op_sel_hi:[1,0]
	v_pk_mul_f32 v[40:41], v[40:41], v[48:49] op_sel_hi:[1,0]
	v_pk_mul_f32 v[42:43], v[42:43], v[48:49] op_sel_hi:[1,0]
	v_pk_mul_f32 v[32:33], v[32:33], v[48:49] op_sel_hi:[1,0]
	v_pk_mul_f32 v[34:35], v[34:35], v[48:49] op_sel_hi:[1,0]
	v_pk_mul_f32 v[148:149], v[44:45], v[144:145] op_sel:[0,1] op_sel_hi:[1,1]
	v_exp_f32_e32 v148, v148
	v_exp_f32_e32 v149, v149
	v_add_f32_e32 v148, 1.0, v148
	v_add_f32_e32 v149, 1.0, v149
	v_rcp_f32_e32 v148, v148
	v_rcp_f32_e32 v149, v149
	s_nop 0
	v_pk_mul_f32 v[44:45], v[44:45], v[148:149]
	v_pk_mul_f32 v[40:41], v[40:41], v[44:45]
	v_pk_mul_f32 v[148:149], v[46:47], v[144:145] op_sel:[0,1] op_sel_hi:[1,1]
	v_exp_f32_e32 v148, v148
	v_exp_f32_e32 v149, v149
	v_add_f32_e32 v148, 1.0, v148
	v_add_f32_e32 v149, 1.0, v149
	v_rcp_f32_e32 v148, v148
	v_rcp_f32_e32 v149, v149
	s_nop 0
	v_pk_mul_f32 v[46:47], v[46:47], v[148:149]
	v_pk_mul_f32 v[42:43], v[42:43], v[46:47]
	v_pk_mul_f32 v[148:149], v[36:37], v[144:145] op_sel:[0,1] op_sel_hi:[1,1]
	v_exp_f32_e32 v148, v148
	v_exp_f32_e32 v149, v149
	v_add_f32_e32 v148, 1.0, v148
	v_add_f32_e32 v149, 1.0, v149
	v_rcp_f32_e32 v148, v148
	v_rcp_f32_e32 v149, v149
	s_nop 0
	v_pk_mul_f32 v[36:37], v[36:37], v[148:149]
	v_pk_mul_f32 v[32:33], v[32:33], v[36:37]
	v_pk_mul_f32 v[148:149], v[38:39], v[144:145] op_sel:[0,1] op_sel_hi:[1,1]
	v_exp_f32_e32 v148, v148
	v_exp_f32_e32 v149, v149
	v_add_f32_e32 v148, 1.0, v148
	v_add_f32_e32 v149, 1.0, v149
	v_rcp_f32_e32 v148, v148
	v_rcp_f32_e32 v149, v149
	s_nop 0
	v_pk_mul_f32 v[38:39], v[38:39], v[148:149]
	v_pk_mul_f32 v[34:35], v[34:35], v[38:39]
	v_cvt_pk_bf16_f32 v35, v34, v35
	v_cvt_pk_bf16_f32 v34, v32, v33
	v_cvt_pk_bf16_f32 v32, v40, v41
	v_cvt_pk_bf16_f32 v33, v42, v43
	v_add_u32_e32 v38, 0x90, v144
	v_mad_i64_i32 v[36:37], s[4:5], v38, s3, v[112:113]
	v_lshl_add_u64 v[36:37], v[36:37], 0, s[0:1]
	v_lshl_add_u64 v[36:37], v[36:37], 0, s[34:35]
	v_lshl_add_u64 v[36:37], v[36:37], 0, v[184:185]
	global_store_dwordx4 v[36:37], v[32:35], off
	ds_read_b32 v32, v142 offset:640
	s_waitcnt lgkmcnt(0)
; __device__ __forceinline__ u32x4 pack8(const f32x4 a, const f32x4 b) { u32x4 w; w.x = cvt_pk_bf16(a[0], a[1]); w.y = cvt_pk_bf16(a[2], a[3]); w.z = cvt_pk_bf16(b[0], b[1]); w.w = cvt_pk_bf16(b[2], b[3]); return w; }
; #define PG8_BAR __builtin_amdgcn_s_barrier()
;     __device__ __forceinline__ void operator()(const f32x4 (&acc)[2][2][4][2], const Unit& u, int wr, int wc, int fr, int fq) const {
;     ...
;                 const float rs = R[ai * HALF + wr * 64 + m * 16 + fr];
;                 bf16_t* ACT = (bf16_t*)(ws + WS_ACT);
;                 f32x4 a[2];
; #pragma unroll
;                 for (int n = 0; n < 2; ++n) {
;                     const f32x4 g = acc[ai][0][m][n] * rs, uu = acc[ai][1][m][n] * rs;
; #pragma unroll
;                     for (int j = 0; j < 4; ++j) a[n][j] = g[j] * __builtin_amdgcn_rcpf(1.0f + __builtin_amdgcn_exp2f(-1.4426950408889634f * g[j])) * uu[j];
;                 }
;                 *(u32x4*)(ACT + (size_t)row * 2816 + u.pn * 128 + wc * 32 + 8 * fq) = pack8(a[0], a[1]);
; template <class Epi, class Sched, bool ALIGN_EPI = false, bool SP2 = false>
; __device__ __forceinline__ void gemm_phase(PG8_LAS unsigned char* lds, const Gemm g, const Sched& S, const Epi& E) {
;     ...
;         if constexpr (!Epi::AFTER_DRAIN) { E(acc, cur, wr, wc, fr, fq); S.done(cur); }
;         if (!has_next) break;
; #pragma unroll
;         for (int a = 0; a < 2; ++a)
; #pragma unroll
;             for (int b = 0; b < 2; ++b)
; #pragma unroll
;                 for (int m = 0; m < 4; ++m)
; #pragma unroll
;                     for (int n = 0; n < 2; ++n) acc[a][b][m][n] = (f32x4){0.f, 0.f, 0.f, 0.f};
;         cur = nxt; cA = nA; cB = nB; ++ui;
;         if constexpr (ALIGN_EPI) { if (wr == 1) PG8_BAR; }
	v_pk_mul_f32 v[28:29], v[28:29], v[32:33] op_sel_hi:[1,0]
	v_pk_mul_f32 v[30:31], v[30:31], v[32:33] op_sel_hi:[1,0]
	v_pk_mul_f32 v[20:21], v[20:21], v[32:33] op_sel_hi:[1,0]
	v_pk_mul_f32 v[22:23], v[22:23], v[32:33] op_sel_hi:[1,0]
	v_pk_mul_f32 v[24:25], v[24:25], v[32:33] op_sel_hi:[1,0]
	v_pk_mul_f32 v[26:27], v[26:27], v[32:33] op_sel_hi:[1,0]
	v_pk_mul_f32 v[16:17], v[16:17], v[32:33] op_sel_hi:[1,0]
	v_pk_mul_f32 v[18:19], v[18:19], v[32:33] op_sel_hi:[1,0]
	v_pk_mul_f32 v[148:149], v[28:29], v[144:145] op_sel:[0,1] op_sel_hi:[1,1]
	v_exp_f32_e32 v148, v148
	v_exp_f32_e32 v149, v149
	v_add_f32_e32 v148, 1.0, v148
	v_add_f32_e32 v149, 1.0, v149
	v_rcp_f32_e32 v148, v148
	v_rcp_f32_e32 v149, v149
	s_nop 0
	v_pk_mul_f32 v[28:29], v[28:29], v[148:149]
	v_pk_mul_f32 v[24:25], v[24:25], v[28:29]
	v_pk_mul_f32 v[148:149], v[30:31], v[144:145] op_sel:[0,1] op_sel_hi:[1,1]
	v_exp_f32_e32 v148, v148
	v_exp_f32_e32 v149, v149
	v_add_f32_e32 v148, 1.0, v148
	v_add_f32_e32 v149, 1.0, v149
	v_rcp_f32_e32 v148, v148
	v_rcp_f32_e32 v149, v149
	s_nop 0
	v_pk_mul_f32 v[30:31], v[30:31], v[148:149]
	v_pk_mul_f32 v[26:27], v[26:27], v[30:31]
	v_pk_mul_f32 v[148:149], v[20:21], v[144:145] op_sel:[0,1] op_sel_hi:[1,1]
	v_exp_f32_e32 v148, v148
	v_exp_f32_e32 v149, v149
	v_add_f32_e32 v148, 1.0, v148
	v_add_f32_e32 v149, 1.0, v149
	v_rcp_f32_e32 v148, v148
	v_rcp_f32_e32 v149, v149
	s_nop 0
	v_pk_mul_f32 v[20:21], v[20:21], v[148:149]
	v_pk_mul_f32 v[16:17], v[16:17], v[20:21]
	v_pk_mul_f32 v[148:149], v[22:23], v[144:145] op_sel:[0,1] op_sel_hi:[1,1]
	v_exp_f32_e32 v148, v148
	v_exp_f32_e32 v149, v149
	v_add_f32_e32 v148, 1.0, v148
	v_add_f32_e32 v149, 1.0, v149
	v_rcp_f32_e32 v148, v148
	v_rcp_f32_e32 v149, v149
	s_nop 0
	v_pk_mul_f32 v[22:23], v[22:23], v[148:149]
	v_pk_mul_f32 v[18:19], v[18:19], v[22:23]
	v_cvt_pk_bf16_f32 v19, v18, v19
	v_cvt_pk_bf16_f32 v18, v16, v17
	v_cvt_pk_bf16_f32 v16, v24, v25
	v_cvt_pk_bf16_f32 v17, v26, v27
	v_add_u32_e32 v22, 0xa0, v144
	v_mad_i64_i32 v[20:21], s[4:5], v22, s3, v[112:113]
	v_lshl_add_u64 v[20:21], v[20:21], 0, s[0:1]
	v_lshl_add_u64 v[20:21], v[20:21], 0, s[34:35]
	v_lshl_add_u64 v[20:21], v[20:21], 0, v[184:185]
	global_store_dwordx4 v[20:21], v[16:19], off
	ds_read_b32 v16, v142 offset:704
	s_waitcnt lgkmcnt(0)
	v_pk_mul_f32 v[12:13], v[12:13], v[16:17] op_sel_hi:[1,0]
	v_pk_mul_f32 v[14:15], v[14:15], v[16:17] op_sel_hi:[1,0]
	v_pk_mul_f32 v[4:5], v[4:5], v[16:17] op_sel_hi:[1,0]
	v_pk_mul_f32 v[6:7], v[6:7], v[16:17] op_sel_hi:[1,0]
	v_pk_mul_f32 v[8:9], v[8:9], v[16:17] op_sel_hi:[1,0]
	v_pk_mul_f32 v[10:11], v[10:11], v[16:17] op_sel_hi:[1,0]
	v_pk_mul_f32 v[0:1], v[0:1], v[16:17] op_sel_hi:[1,0]
	v_pk_mul_f32 v[2:3], v[2:3], v[16:17] op_sel_hi:[1,0]
	v_pk_mul_f32 v[148:149], v[12:13], v[144:145] op_sel:[0,1] op_sel_hi:[1,1]
	v_exp_f32_e32 v148, v148
	v_exp_f32_e32 v149, v149
	v_add_f32_e32 v148, 1.0, v148
	v_add_f32_e32 v149, 1.0, v149
	v_rcp_f32_e32 v148, v148
	v_rcp_f32_e32 v149, v149
	s_nop 0
	v_pk_mul_f32 v[12:13], v[12:13], v[148:149]
	v_pk_mul_f32 v[8:9], v[8:9], v[12:13]
	v_pk_mul_f32 v[148:149], v[14:15], v[144:145] op_sel:[0,1] op_sel_hi:[1,1]
	v_exp_f32_e32 v148, v148
	v_exp_f32_e32 v149, v149
	v_add_f32_e32 v148, 1.0, v148
	v_add_f32_e32 v149, 1.0, v149
	v_rcp_f32_e32 v148, v148
	v_rcp_f32_e32 v149, v149
	s_nop 0
	v_pk_mul_f32 v[14:15], v[14:15], v[148:149]
	v_pk_mul_f32 v[10:11], v[10:11], v[14:15]
	v_pk_mul_f32 v[148:149], v[4:5], v[144:145] op_sel:[0,1] op_sel_hi:[1,1]
	v_exp_f32_e32 v148, v148
	v_exp_f32_e32 v149, v149
	v_add_f32_e32 v148, 1.0, v148
	v_add_f32_e32 v149, 1.0, v149
	v_rcp_f32_e32 v148, v148
	v_rcp_f32_e32 v149, v149
	s_nop 0
	v_pk_mul_f32 v[4:5], v[4:5], v[148:149]
	v_pk_mul_f32 v[0:1], v[0:1], v[4:5]
	v_pk_mul_f32 v[148:149], v[6:7], v[144:145] op_sel:[0,1] op_sel_hi:[1,1]
	v_exp_f32_e32 v148, v148
	v_exp_f32_e32 v149, v149
	v_add_f32_e32 v148, 1.0, v148
	v_add_f32_e32 v149, 1.0, v149
	v_rcp_f32_e32 v148, v148
	v_rcp_f32_e32 v149, v149
	s_nop 0
	v_pk_mul_f32 v[6:7], v[6:7], v[148:149]
	v_pk_mul_f32 v[2:3], v[2:3], v[6:7]
	v_cvt_pk_bf16_f32 v3, v2, v3
	v_cvt_pk_bf16_f32 v2, v0, v1
	v_cvt_pk_bf16_f32 v0, v8, v9
	v_cvt_pk_bf16_f32 v1, v10, v11
	v_add_u32_e32 v6, 0xb0, v144
	v_mad_i64_i32 v[4:5], s[4:5], v6, s3, v[112:113]
	v_lshl_add_u64 v[4:5], v[4:5], 0, s[0:1]
	v_lshl_add_u64 v[4:5], v[4:5], 0, s[34:35]
	v_lshl_add_u64 v[4:5], v[4:5], 0, v[184:185]
	s_mov_b64 s[0:1], -1
	global_store_dwordx4 v[4:5], v[0:3], off
	s_cbranch_vccnz .LBB0_31
	s_andn2_b64 vcc, exec, s[8:9]
	s_cbranch_vccnz .LBB0_30
	s_barrier
	s_branch .LBB0_30

; #define PG8_STAGE(bufoff, gbase, voff) do { _Pragma("unroll") for (int _i = 0; _i < 2; ++_i) \
;         __builtin_amdgcn_global_load_lds((const unsigned*)((const char*)(gbase) + (voff)[_i]), (PG8_LAS unsigned*)(lds + (bufoff) + ldsw + _i * 8192), 16, 0, 0); } while (0)
; #define PG8_LDA(dst, b, h) do { _Pragma("unroll") for (int m = 0; m < 4; ++m) _Pragma("unroll") for (int k = 0; k < 2; ++k) dst[m][k] = *(const PG8_LAS bf16x8*)(lds + PG8_SA(b, h) + aoff + m * 2048 + k * 1024); } while (0)
; #define PG8_LDB(dst, b, h) do { _Pragma("unroll") for (int n = 0; n < 2; ++n) _Pragma("unroll") for (int k = 0; k < 2; ++k) dst[n][k] = *(const PG8_LAS bf16x8*)(lds + PG8_SB(b, h) + boff + n * 2048 + k * 1024); } while (0)
; #define PG8_MMA(ai, bj, At, Bt) do { __builtin_amdgcn_s_setprio(1); _Pragma("unroll") for (int m = 0; m < 4; ++m) _Pragma("unroll") for (int n = 0; n < 2; ++n) _Pragma("unroll") for (int k = 0; k < 2; ++k) \
;         acc[ai][bj][m][n] = __builtin_amdgcn_mfma_f32_16x16x32_bf16(Bt[n][k], At[m][k], acc[ai][bj][m][n], 0, 0, 0); __builtin_amdgcn_s_setprio(0); } while (0)
; #define PG8_WAIT_V(n) asm volatile("s_waitcnt vmcnt(" #n ")" ::: "memory")
; template <class Epi, class Sched, bool ALIGN_EPI = false, bool SP2 = false>
; __device__ __forceinline__ void gemm_phase(PG8_LAS unsigned char* lds, const Gemm g, const Sched& S, const Epi& E) {
;     ...
;             PG8_LDB(B0, 0, 0); PG8_LDB(B1, 0, 1); PG8_SCHED; PG8_LDA(At, 0, 0); PG8_STAGE(PG8_SA(1, 1), a1 + hstep, voffA);
;             PG8_WAIT_V(8); PG8_WAIT_L(0); PG8_BAR; PG8_MMA(0, 0, At, B0); PG8_MMA(0, 1, At, B1); PG8_BAR; PG8_SCHED;
;             PG8_LDA(At, 0, 1); PG8_STAGE(PG8_SB(0, 0), b2, voffB); PG8_STAGE(PG8_SB(0, 1), b2 + hstep, voffB); PG8_STAGE(PG8_SA(0, 0), a2, voffA);
;             PG8_WAIT_V(8); PG8_WAIT_L(0); PG8_BAR; PG8_MMA(1, 0, At, B0); PG8_MMA(1, 1, At, B1); PG8_BAR; PG8_SCHED;
;             PG8_LDB(B0, 1, 0); PG8_LDB(B1, 1, 1); PG8_SCHED; PG8_LDA(At, 1, 0); PG8_STAGE(PG8_SA(0, 1), a2 + hstep, voffA);
;             PG8_WAIT_V(8); PG8_WAIT_L(0); PG8_BAR; PG8_MMA(0, 0, At, B0); PG8_MMA(0, 1, At, B1); PG8_BAR; PG8_SCHED;
;             PG8_LDA(At, 1, 1); PG8_STAGE(PG8_SB(1, 0), b3, voffB); PG8_STAGE(PG8_SB(1, 1), b3 + hstep, voffB); PG8_STAGE(PG8_SA(1, 0), a3, voffA);
;             PG8_WAIT_V(8); PG8_WAIT_L(0); PG8_BAR; PG8_MMA(1, 0, At, B0); PG8_MMA(1, 1, At, B1); PG8_BAR; PG8_SCHED;
.LBB0_218:
	s_add_u32 s25, s0, 0xfffc0080
	s_addc_u32 s40, s1, -1
	s_cmp_eq_u32 s93, 12
	s_cselect_b32 s43, s4, s40
	s_cselect_b32 s42, s5, s25
	s_cselect_b32 s41, s27, s92
	s_cselect_b32 s40, s58, s59
	s_add_i32 s94, 0, 0x10000
	s_add_i32 s25, 0, 0x14000
	v_add_u32_e32 v140, s94, v228
	v_add_u32_e32 v156, s25, v228
	ds_read_b128 v[128:131], v140
	ds_read_b128 v[132:135], v140 offset:1024
	ds_read_b128 v[136:139], v140 offset:2048
	ds_read_b128 v[140:143], v140 offset:3072
	ds_read_b128 v[144:147], v156
	ds_read_b128 v[148:151], v156 offset:1024
	ds_read_b128 v[152:155], v156 offset:2048
	ds_read_b128 v[156:159], v156 offset:3072
	s_add_i32 m0, s45, 0xc000
	ds_read_b128 v[160:163], v230
	ds_read_b128 v[164:167], v230 offset:1024
	ds_read_b128 v[168:171], v230 offset:2048
	ds_read_b128 v[172:175], v230 offset:3072
	ds_read_b128 v[176:179], v230 offset:4096
	ds_read_b128 v[180:183], v230 offset:5120
	ds_read_b128 v[204:207], v230 offset:6144
	ds_read_b128 v[208:211], v230 offset:7168
	ds_read_b128 v[212:215], v249
	ds_read_b128 v[232:235], v249 offset:1024
	global_load_lds_dwordx4 v198, s[0:1]
	s_add_i32 m0, s45, 0xe000
	s_nop 0
	global_load_lds_dwordx4 v196, s[0:1]
	s_nop 0
	s_waitcnt vmcnt(9)
	s_waitcnt lgkmcnt(0)
	s_barrier
	s_setprio 1
	s_waitcnt lgkmcnt(0)
	v_mfma_f32_16x16x32_bf16 v[124:127], v[128:131], v[160:163], v[124:127]
	v_mfma_f32_16x16x32_bf16 v[120:123], v[136:139], v[160:163], v[120:123]
	v_mfma_f32_16x16x32_bf16 v[108:111], v[128:131], v[168:171], v[108:111]
	v_mfma_f32_16x16x32_bf16 v[104:107], v[136:139], v[168:171], v[104:107]
	v_mfma_f32_16x16x32_bf16 v[92:95], v[128:131], v[176:179], v[92:95]
	v_mfma_f32_16x16x32_bf16 v[88:91], v[136:139], v[176:179], v[88:91]
	v_mfma_f32_16x16x32_bf16 v[76:79], v[128:131], v[204:207], v[76:79]
	v_mfma_f32_16x16x32_bf16 v[72:75], v[136:139], v[204:207], v[72:75]
	v_mfma_f32_16x16x32_bf16 v[124:127], v[132:135], v[164:167], v[124:127]
	v_mfma_f32_16x16x32_bf16 v[120:123], v[140:143], v[164:167], v[120:123]
	v_mfma_f32_16x16x32_bf16 v[108:111], v[132:135], v[172:175], v[108:111]
	v_mfma_f32_16x16x32_bf16 v[104:107], v[140:143], v[172:175], v[104:107]
	v_mfma_f32_16x16x32_bf16 v[92:95], v[132:135], v[180:183], v[92:95]
	v_mfma_f32_16x16x32_bf16 v[88:91], v[140:143], v[180:183], v[88:91]
	v_mfma_f32_16x16x32_bf16 v[76:79], v[132:135], v[208:211], v[76:79]
	v_mfma_f32_16x16x32_bf16 v[72:75], v[140:143], v[208:211], v[72:75]
	s_setprio 0
	s_setprio 1
	v_mfma_f32_16x16x32_bf16 v[116:119], v[144:147], v[160:163], v[116:119]
	v_mfma_f32_16x16x32_bf16 v[112:115], v[152:155], v[160:163], v[112:115]
	v_mfma_f32_16x16x32_bf16 v[100:103], v[144:147], v[168:171], v[100:103]
	v_mfma_f32_16x16x32_bf16 v[96:99], v[152:155], v[168:171], v[96:99]
	v_mfma_f32_16x16x32_bf16 v[84:87], v[144:147], v[176:179], v[84:87]
	v_mfma_f32_16x16x32_bf16 v[80:83], v[152:155], v[176:179], v[80:83]
	v_mfma_f32_16x16x32_bf16 v[68:71], v[144:147], v[204:207], v[68:71]
	v_mfma_f32_16x16x32_bf16 v[64:67], v[152:155], v[204:207], v[64:67]
	v_mfma_f32_16x16x32_bf16 v[116:119], v[148:151], v[164:167], v[116:119]
	v_mfma_f32_16x16x32_bf16 v[112:115], v[156:159], v[164:167], v[112:115]
	v_mfma_f32_16x16x32_bf16 v[100:103], v[148:151], v[172:175], v[100:103]
	v_mfma_f32_16x16x32_bf16 v[96:99], v[156:159], v[172:175], v[96:99]
	v_mfma_f32_16x16x32_bf16 v[84:87], v[148:151], v[180:183], v[84:87]
	v_mfma_f32_16x16x32_bf16 v[80:83], v[156:159], v[180:183], v[80:83]
	v_mfma_f32_16x16x32_bf16 v[68:71], v[148:151], v[208:211], v[68:71]
	v_mfma_f32_16x16x32_bf16 v[64:67], v[156:159], v[208:211], v[64:67]
	v_mfma_f32_16x16x32_bf16 v[236:239], v[128:131], v[212:215], v[236:239]
	v_mfma_f32_16x16x32_bf16 v[240:243], v[136:139], v[212:215], v[240:243]
	v_mfma_f32_16x16x32_bf16 v[244:247], v[144:147], v[212:215], v[244:247]
	v_mfma_f32_16x16x32_bf16 v[200:203], v[152:155], v[212:215], v[200:203]
	v_mfma_f32_16x16x32_bf16 v[236:239], v[132:135], v[232:235], v[236:239]
	v_mfma_f32_16x16x32_bf16 v[240:243], v[140:143], v[232:235], v[240:243]
	v_mfma_f32_16x16x32_bf16 v[244:247], v[148:151], v[232:235], v[244:247]
	v_mfma_f32_16x16x32_bf16 v[200:203], v[156:159], v[232:235], v[200:203]
	s_setprio 0
	s_barrier
	s_add_i32 s94, s94, s44
	s_mov_b32 m0, s94
	ds_read_b128 v[160:163], v230 offset:16384
	ds_read_b128 v[164:167], v230 offset:17408
	ds_read_b128 v[168:171], v230 offset:18432
	ds_read_b128 v[172:175], v230 offset:19456
	ds_read_b128 v[176:179], v230 offset:20480
	ds_read_b128 v[180:183], v230 offset:21504
	ds_read_b128 v[204:207], v230 offset:22528
	ds_read_b128 v[208:211], v230 offset:23552
	global_load_lds_dwordx4 v184, s[40:41]
	s_add_i32 m0, s94, 0x2000
	s_add_u32 s98, s40, 0x40000
	s_addc_u32 s99, s41, 0
	s_add_i32 s25, s25, s44
	global_load_lds_dwordx4 v194, s[40:41]
	s_mov_b32 m0, s25
	s_nop 0
	global_load_lds_dwordx4 v184, s[98:99]
	s_add_i32 m0, s25, 0x2000
	s_nop 0
	global_load_lds_dwordx4 v194, s[98:99]
	s_mov_b32 m0, s45
	s_nop 0
	global_load_lds_dwordx4 v198, s[42:43]
	s_mov_b32 m0, s46
	s_nop 0
	global_load_lds_dwordx4 v196, s[42:43]
	s_and_b32 m0, s44, 0xc00
	s_add_i32 m0, m0, 0x20800
	s_nop 0
	global_load_lds_dwordx4 v248, s[42:43]
	s_nop 0
	s_waitcnt vmcnt(9)
	s_waitcnt lgkmcnt(0)
	s_barrier
; #define PG8_STAGE(bufoff, gbase, voff) do { _Pragma("unroll") for (int _i = 0; _i < 2; ++_i) \
;         __builtin_amdgcn_global_load_lds((const unsigned*)((const char*)(gbase) + (voff)[_i]), (PG8_LAS unsigned*)(lds + (bufoff) + ldsw + _i * 8192), 16, 0, 0); } while (0)
; #define PG8_LDA(dst, b, h) do { _Pragma("unroll") for (int m = 0; m < 4; ++m) _Pragma("unroll") for (int k = 0; k < 2; ++k) dst[m][k] = *(const PG8_LAS bf16x8*)(lds + PG8_SA(b, h) + aoff + m * 2048 + k * 1024); } while (0)
; #define PG8_LDB(dst, b, h) do { _Pragma("unroll") for (int n = 0; n < 2; ++n) _Pragma("unroll") for (int k = 0; k < 2; ++k) dst[n][k] = *(const PG8_LAS bf16x8*)(lds + PG8_SB(b, h) + boff + n * 2048 + k * 1024); } while (0)
; #define PG8_MMA(ai, bj, At, Bt) do { __builtin_amdgcn_s_setprio(1); _Pragma("unroll") for (int m = 0; m < 4; ++m) _Pragma("unroll") for (int n = 0; n < 2; ++n) _Pragma("unroll") for (int k = 0; k < 2; ++k) \
;         acc[ai][bj][m][n] = __builtin_amdgcn_mfma_f32_16x16x32_bf16(Bt[n][k], At[m][k], acc[ai][bj][m][n], 0, 0, 0); __builtin_amdgcn_s_setprio(0); } while (0)
; #define PG8_WAIT_V(n) asm volatile("s_waitcnt vmcnt(" #n ")" ::: "memory")
; #define PG8_WAIT_L(n) asm volatile("s_waitcnt lgkmcnt(" #n ")" ::: "memory")
; #define PG8_BAR __builtin_amdgcn_s_barrier()
; #define PG8_SCHED __builtin_amdgcn_sched_barrier(0)
; template <class Epi, class Sched, bool ALIGN_EPI = false, bool SP2 = false>
; __device__ __forceinline__ void gemm_phase(PG8_LAS unsigned char* lds, const Gemm g, const Sched& S, const Epi& E) {
;     ...
;             PG8_WAIT_V(8); PG8_WAIT_L(0); PG8_BAR; PG8_MMA(1, 0, At, B0); PG8_MMA(1, 1, At, B1); PG8_BAR; PG8_SCHED;
;             PG8_LDB(B0, 1, 0); PG8_LDB(B1, 1, 1); PG8_SCHED; PG8_LDA(At, 1, 0); PG8_STAGE(PG8_SA(0, 1), a2 + hstep, voffA);
;             PG8_WAIT_V(8); PG8_WAIT_L(0); PG8_BAR; PG8_MMA(0, 0, At, B0); PG8_MMA(0, 1, At, B1); PG8_BAR; PG8_SCHED;
;             PG8_LDA(At, 1, 1); PG8_STAGE(PG8_SB(1, 0), b3, voffB); PG8_STAGE(PG8_SB(1, 1), b3 + hstep, voffB); PG8_STAGE(PG8_SA(1, 0), a3, voffA);
	s_setprio 1
	s_waitcnt lgkmcnt(0)
	v_mfma_f32_16x16x32_bf16 v[60:63], v[128:131], v[160:163], v[60:63]
	v_mfma_f32_16x16x32_bf16 v[56:59], v[136:139], v[160:163], v[56:59]
	v_mfma_f32_16x16x32_bf16 v[44:47], v[128:131], v[168:171], v[44:47]
	v_mfma_f32_16x16x32_bf16 v[40:43], v[136:139], v[168:171], v[40:43]
	v_mfma_f32_16x16x32_bf16 v[28:31], v[128:131], v[176:179], v[28:31]
	v_mfma_f32_16x16x32_bf16 v[24:27], v[136:139], v[176:179], v[24:27]
	v_mfma_f32_16x16x32_bf16 v[12:15], v[128:131], v[204:207], v[12:15]
	v_mfma_f32_16x16x32_bf16 v[8:11], v[136:139], v[204:207], v[8:11]
	v_mfma_f32_16x16x32_bf16 v[60:63], v[132:135], v[164:167], v[60:63]
	v_mfma_f32_16x16x32_bf16 v[56:59], v[140:143], v[164:167], v[56:59]
	v_mfma_f32_16x16x32_bf16 v[44:47], v[132:135], v[172:175], v[44:47]
	v_mfma_f32_16x16x32_bf16 v[40:43], v[140:143], v[172:175], v[40:43]
	v_mfma_f32_16x16x32_bf16 v[28:31], v[132:135], v[180:183], v[28:31]
	v_mfma_f32_16x16x32_bf16 v[24:27], v[140:143], v[180:183], v[24:27]
	v_mfma_f32_16x16x32_bf16 v[12:15], v[132:135], v[208:211], v[12:15]
	v_mfma_f32_16x16x32_bf16 v[8:11], v[140:143], v[208:211], v[8:11]
	s_setprio 0
	s_setprio 1
	v_mfma_f32_16x16x32_bf16 v[52:55], v[144:147], v[160:163], v[52:55]
	v_mfma_f32_16x16x32_bf16 v[48:51], v[152:155], v[160:163], v[48:51]
	v_mfma_f32_16x16x32_bf16 v[36:39], v[144:147], v[168:171], v[36:39]
	v_mfma_f32_16x16x32_bf16 v[32:35], v[152:155], v[168:171], v[32:35]
	v_mfma_f32_16x16x32_bf16 v[20:23], v[144:147], v[176:179], v[20:23]
	v_mfma_f32_16x16x32_bf16 v[16:19], v[152:155], v[176:179], v[16:19]
	v_mfma_f32_16x16x32_bf16 v[4:7], v[144:147], v[204:207], v[4:7]
	v_mfma_f32_16x16x32_bf16 v[0:3], v[152:155], v[204:207], v[0:3]
	v_mfma_f32_16x16x32_bf16 v[52:55], v[148:151], v[164:167], v[52:55]
	v_mfma_f32_16x16x32_bf16 v[48:51], v[156:159], v[164:167], v[48:51]
	v_mfma_f32_16x16x32_bf16 v[36:39], v[148:151], v[172:175], v[36:39]
	v_mfma_f32_16x16x32_bf16 v[32:35], v[156:159], v[172:175], v[32:35]
	v_mfma_f32_16x16x32_bf16 v[20:23], v[148:151], v[180:183], v[20:23]
	v_mfma_f32_16x16x32_bf16 v[16:19], v[156:159], v[180:183], v[16:19]
	v_mfma_f32_16x16x32_bf16 v[4:7], v[148:151], v[208:211], v[4:7]
	v_mfma_f32_16x16x32_bf16 v[0:3], v[156:159], v[208:211], v[0:3]
	s_setprio 0
	s_barrier
	s_add_i32 s25, 0, 0x18000
	s_add_i32 s94, 0, 0x1c000
	v_add_u32_e32 v140, s25, v228
	v_add_u32_e32 v156, s94, v228
	ds_read_b128 v[128:131], v140
	ds_read_b128 v[132:135], v140 offset:1024
	ds_read_b128 v[136:139], v140 offset:2048
	ds_read_b128 v[140:143], v140 offset:3072
	ds_read_b128 v[144:147], v156
	ds_read_b128 v[148:151], v156 offset:1024
	ds_read_b128 v[152:155], v156 offset:2048
	ds_read_b128 v[156:159], v156 offset:3072
	s_add_u32 s98, s42, 0x40000
	s_addc_u32 s99, s43, 0
	s_mov_b32 m0, s47
	ds_read_b128 v[160:163], v230 offset:32768
	ds_read_b128 v[164:167], v230 offset:33792
	ds_read_b128 v[168:171], v230 offset:34816
	ds_read_b128 v[172:175], v230 offset:35840
	ds_read_b128 v[176:179], v230 offset:36864
	ds_read_b128 v[180:183], v230 offset:37888
	ds_read_b128 v[204:207], v230 offset:38912
	ds_read_b128 v[208:211], v230 offset:39936
	ds_read_b128 v[212:215], v249 offset:4096
	ds_read_b128 v[232:235], v249 offset:5120
	global_load_lds_dwordx4 v198, s[98:99]
	s_mov_b32 m0, s48
	s_nop 0
	global_load_lds_dwordx4 v196, s[98:99]
	s_nop 0
	s_waitcnt vmcnt(9)
	s_waitcnt lgkmcnt(0)
	s_barrier
; #define PG8_STAGE(bufoff, gbase, voff) do { _Pragma("unroll") for (int _i = 0; _i < 2; ++_i) \
;         __builtin_amdgcn_global_load_lds((const unsigned*)((const char*)(gbase) + (voff)[_i]), (PG8_LAS unsigned*)(lds + (bufoff) + ldsw + _i * 8192), 16, 0, 0); } while (0)
; #define PG8_LDA(dst, b, h) do { _Pragma("unroll") for (int m = 0; m < 4; ++m) _Pragma("unroll") for (int k = 0; k < 2; ++k) dst[m][k] = *(const PG8_LAS bf16x8*)(lds + PG8_SA(b, h) + aoff + m * 2048 + k * 1024); } while (0)
; #define PG8_MMA(ai, bj, At, Bt) do { __builtin_amdgcn_s_setprio(1); _Pragma("unroll") for (int m = 0; m < 4; ++m) _Pragma("unroll") for (int n = 0; n < 2; ++n) _Pragma("unroll") for (int k = 0; k < 2; ++k) \
;         acc[ai][bj][m][n] = __builtin_amdgcn_mfma_f32_16x16x32_bf16(Bt[n][k], At[m][k], acc[ai][bj][m][n], 0, 0, 0); __builtin_amdgcn_s_setprio(0); } while (0)
; #define PG8_WAIT_V(n) asm volatile("s_waitcnt vmcnt(" #n ")" ::: "memory")
; #define PG8_WAIT_L(n) asm volatile("s_waitcnt lgkmcnt(" #n ")" ::: "memory")
; #define PG8_BAR __builtin_amdgcn_s_barrier()
; #define PG8_SCHED __builtin_amdgcn_sched_barrier(0)
;     __device__ __forceinline__ void operator()(const f32x4 (&acc)[2][2][4][2], const Unit& u, int wr, int wc, int fr, int fq) const {
;     ...
;                 const int row = u.pm * BM + ai * HALF + wr * 64 + m * 16 + fr;
;                 const float* bp = (u.pm < 64) ? base_p + (size_t)row * 1024 : base_s + (size_t)(row - E_MP) * 1024;
; #pragma unroll
;                 for (int bj = 0; bj < 2; ++bj) { bv[m][bj][0] = *(const f32x4*)(bp + col0 + bj * HALF); bv[m][bj][1] = *(const f32x4*)(bp + col0 + bj * HALF + 4); }
; template <class Epi, class Sched, bool ALIGN_EPI = false, bool SP2 = false>
; __device__ __forceinline__ void gemm_phase(PG8_LAS unsigned char* lds, const Gemm g, const Sched& S, const Epi& E) {
;     ...
;             PG8_WAIT_V(8); PG8_WAIT_L(0); PG8_BAR; PG8_MMA(0, 0, At, B0); PG8_MMA(0, 1, At, B1); PG8_BAR; PG8_SCHED;
;             PG8_LDA(At, 1, 1); PG8_STAGE(PG8_SB(1, 0), b3, voffB); PG8_STAGE(PG8_SB(1, 1), b3 + hstep, voffB); PG8_STAGE(PG8_SA(1, 0), a3, voffA);
;             PG8_WAIT_V(8); PG8_WAIT_L(0); PG8_BAR; PG8_MMA(1, 0, At, B0); PG8_MMA(1, 1, At, B1); PG8_BAR; PG8_SCHED;
	s_setprio 1
	s_waitcnt lgkmcnt(0)
	v_mfma_f32_16x16x32_bf16 v[124:127], v[128:131], v[160:163], v[124:127]
	v_mfma_f32_16x16x32_bf16 v[120:123], v[136:139], v[160:163], v[120:123]
	v_mfma_f32_16x16x32_bf16 v[108:111], v[128:131], v[168:171], v[108:111]
	v_mfma_f32_16x16x32_bf16 v[104:107], v[136:139], v[168:171], v[104:107]
	v_mfma_f32_16x16x32_bf16 v[92:95], v[128:131], v[176:179], v[92:95]
	v_mfma_f32_16x16x32_bf16 v[88:91], v[136:139], v[176:179], v[88:91]
	v_mfma_f32_16x16x32_bf16 v[76:79], v[128:131], v[204:207], v[76:79]
	v_mfma_f32_16x16x32_bf16 v[72:75], v[136:139], v[204:207], v[72:75]
	v_mfma_f32_16x16x32_bf16 v[124:127], v[132:135], v[164:167], v[124:127]
	v_mfma_f32_16x16x32_bf16 v[120:123], v[140:143], v[164:167], v[120:123]
	v_mfma_f32_16x16x32_bf16 v[108:111], v[132:135], v[172:175], v[108:111]
	v_mfma_f32_16x16x32_bf16 v[104:107], v[140:143], v[172:175], v[104:107]
	v_mfma_f32_16x16x32_bf16 v[92:95], v[132:135], v[180:183], v[92:95]
	v_mfma_f32_16x16x32_bf16 v[88:91], v[140:143], v[180:183], v[88:91]
	v_mfma_f32_16x16x32_bf16 v[76:79], v[132:135], v[208:211], v[76:79]
	v_mfma_f32_16x16x32_bf16 v[72:75], v[140:143], v[208:211], v[72:75]
	s_setprio 0
	s_setprio 1
	v_mfma_f32_16x16x32_bf16 v[116:119], v[144:147], v[160:163], v[116:119]
	v_mfma_f32_16x16x32_bf16 v[112:115], v[152:155], v[160:163], v[112:115]
	v_mfma_f32_16x16x32_bf16 v[100:103], v[144:147], v[168:171], v[100:103]
	v_mfma_f32_16x16x32_bf16 v[96:99], v[152:155], v[168:171], v[96:99]
	v_mfma_f32_16x16x32_bf16 v[84:87], v[144:147], v[176:179], v[84:87]
	v_mfma_f32_16x16x32_bf16 v[80:83], v[152:155], v[176:179], v[80:83]
	v_mfma_f32_16x16x32_bf16 v[68:71], v[144:147], v[204:207], v[68:71]
	v_mfma_f32_16x16x32_bf16 v[64:67], v[152:155], v[204:207], v[64:67]
	v_mfma_f32_16x16x32_bf16 v[116:119], v[148:151], v[164:167], v[116:119]
	v_mfma_f32_16x16x32_bf16 v[112:115], v[156:159], v[164:167], v[112:115]
	v_mfma_f32_16x16x32_bf16 v[100:103], v[148:151], v[172:175], v[100:103]
	v_mfma_f32_16x16x32_bf16 v[96:99], v[156:159], v[172:175], v[96:99]
	v_mfma_f32_16x16x32_bf16 v[84:87], v[148:151], v[180:183], v[84:87]
	v_mfma_f32_16x16x32_bf16 v[80:83], v[156:159], v[180:183], v[80:83]
	v_mfma_f32_16x16x32_bf16 v[68:71], v[148:151], v[208:211], v[68:71]
	v_mfma_f32_16x16x32_bf16 v[64:67], v[156:159], v[208:211], v[64:67]
	v_mfma_f32_16x16x32_bf16 v[236:239], v[128:131], v[212:215], v[236:239]
	v_mfma_f32_16x16x32_bf16 v[240:243], v[136:139], v[212:215], v[240:243]
	v_mfma_f32_16x16x32_bf16 v[244:247], v[144:147], v[212:215], v[244:247]
	v_mfma_f32_16x16x32_bf16 v[200:203], v[152:155], v[212:215], v[200:203]
	v_mfma_f32_16x16x32_bf16 v[236:239], v[132:135], v[232:235], v[236:239]
	v_mfma_f32_16x16x32_bf16 v[240:243], v[140:143], v[232:235], v[240:243]
	v_mfma_f32_16x16x32_bf16 v[244:247], v[148:151], v[232:235], v[244:247]
	v_mfma_f32_16x16x32_bf16 v[200:203], v[156:159], v[232:235], v[200:203]
	s_setprio 0
	s_barrier
	s_add_i32 s25, s25, s44
	s_add_u32 s98, s40, 0x80
	s_addc_u32 s99, s41, 0
	s_mov_b32 m0, s25
	ds_read_b128 v[160:163], v230 offset:49152
	ds_read_b128 v[164:167], v230 offset:50176
	ds_read_b128 v[168:171], v230 offset:51200
	ds_read_b128 v[172:175], v230 offset:52224
	ds_read_b128 v[176:179], v230 offset:53248
	ds_read_b128 v[180:183], v230 offset:54272
	ds_read_b128 v[204:207], v230 offset:55296
	ds_read_b128 v[208:211], v230 offset:56320
	global_load_lds_dwordx4 v184, s[98:99]
	s_add_i32 m0, s25, 0x2000
	s_add_u32 s100, s40, 0x40080
	s_addc_u32 s101, s41, 0
	s_add_i32 s94, s94, s44
	global_load_lds_dwordx4 v194, s[98:99]
	s_mov_b32 m0, s94
	s_add_u32 s98, s42, 0x80
	s_addc_u32 s99, s43, 0
	global_load_lds_dwordx4 v184, s[100:101]
	s_add_i32 m0, s94, 0x2000
	s_nop 0
	global_load_lds_dwordx4 v194, s[100:101]
	s_mov_b32 m0, s51
	s_nop 0
	global_load_lds_dwordx4 v198, s[98:99]
	s_mov_b32 m0, s52
	s_nop 0
	global_load_lds_dwordx4 v196, s[98:99]
	s_and_b32 m0, s44, 0xc00
	s_add_i32 m0, m0, 0x21800
	s_nop 0
	global_load_lds_dwordx4 v248, s[98:99]
	s_waitcnt vmcnt(9)
	s_waitcnt lgkmcnt(0)
	s_barrier
	s_setprio 1
	s_waitcnt lgkmcnt(0)
	v_mfma_f32_16x16x32_bf16 v[60:63], v[128:131], v[160:163], v[60:63]
	v_mfma_f32_16x16x32_bf16 v[56:59], v[136:139], v[160:163], v[56:59]
	v_mfma_f32_16x16x32_bf16 v[44:47], v[128:131], v[168:171], v[44:47]
	v_mfma_f32_16x16x32_bf16 v[40:43], v[136:139], v[168:171], v[40:43]
	v_mfma_f32_16x16x32_bf16 v[28:31], v[128:131], v[176:179], v[28:31]
	v_mfma_f32_16x16x32_bf16 v[24:27], v[136:139], v[176:179], v[24:27]
	v_mfma_f32_16x16x32_bf16 v[12:15], v[128:131], v[204:207], v[12:15]
	v_mfma_f32_16x16x32_bf16 v[8:11], v[136:139], v[204:207], v[8:11]
	v_mfma_f32_16x16x32_bf16 v[60:63], v[132:135], v[164:167], v[60:63]
	v_mfma_f32_16x16x32_bf16 v[56:59], v[140:143], v[164:167], v[56:59]
	v_mfma_f32_16x16x32_bf16 v[44:47], v[132:135], v[172:175], v[44:47]
	v_mfma_f32_16x16x32_bf16 v[40:43], v[140:143], v[172:175], v[40:43]
	v_mfma_f32_16x16x32_bf16 v[28:31], v[132:135], v[180:183], v[28:31]
	v_mfma_f32_16x16x32_bf16 v[24:27], v[140:143], v[180:183], v[24:27]
	v_mfma_f32_16x16x32_bf16 v[12:15], v[132:135], v[208:211], v[12:15]
	v_mfma_f32_16x16x32_bf16 v[8:11], v[140:143], v[208:211], v[8:11]
	s_setprio 0
	s_cmp_eq_u32 s93, 12
	s_cbranch_scc0 .Lxr_skip_218
	s_mul_i32 s98, s56, 0x120
	s_addk_i32 s98, 0x100
	v_and_b32_e32 v190, 15, v227
	v_lshrrev_b32_e32 v191, 6, v227
	v_lshl_add_u32 v190, v191, 4, v190
	v_add_u32_e32 v190, s98, v190
	s_cmp_lt_i32 s56, 56
	s_cselect_b32 s98, s50, s34
	s_cselect_b32 s99, s49, s7
	s_cselect_b32 s100, 0, 0x4000
	v_subrev_u32_e32 v190, s100, v190
	v_mov_b32_e32 v191, 0
	v_lshlrev_b64 v[190:191], 12, v[190:191]
	v_lshl_add_u64 v[190:191], s[98:99], 0, v[190:191]
	v_lshl_or_b32 v217, s57, 8, v229
	v_lshlrev_b32_e32 v217, 2, v217
	v_add_co_u32_e32 v190, vcc, v190, v217
	s_nop 1
	v_addc_co_u32_e32 v191, vcc, 0, v191, vcc
	global_load_dwordx4 v[128:131], v[190:191], off
	global_load_dwordx4 v[132:135], v[190:191], off offset:16
	global_load_dwordx4 v[136:139], v[190:191], off offset:512
	global_load_dwordx4 v[140:143], v[190:191], off offset:528
